# attention work queue: next item claimed at the end of the key loop (thread 0, parked in a VGPR) so the atomic round trip overlaps the item epilogue
# speedup vs baseline: 1.1047x; 1.0006x over previous
; DI int swap23(int r) { return (r & 0x13) | ((r & 4) << 1) | ((r & 8) >> 1); }
;   DI void init_offs() {
; #pragma unroll
;     for (int q = 0; q < NKL; ++q) {
;       const int c = tid + 256 * q, row = c / KCH, cc = c % KCH;
;       koff[q] = (DQK == 96 && cc >= 8) ? row * 32 + (cc - 8) * 8 : row * kpitch + cc * 8;
;     }
; #pragma unroll
;     for (int q = 0; q < 2; ++q) { const int c = tid + 256 * q, dv = c >> 3, kc = c & 7; voff[q] = dv * MPAD + kc * 8; }
;   }
; template <int DQK>
; DI void attn_item(const u16* __restrict__ Qb, int qpitch, const u16* __restrict__ Kb, int kpitch, const u16* __restrict__ KPEb,
;                   const u16* __restrict__ Vt, float* __restrict__ ssq, int rowq0, int rowk0, int nt, char* smem, int tid, bool dry) {
;   typedef AttnCtx<DQK> C;
;   C c;
;   const int lane = tid & 63, wave = tid >> 6, r = lane & 31, h = lane >> 5;
;   c.Kb = Kb; c.KPEb = KPEb; c.Vt = Vt; c.kpitch = kpitch; c.rowk0 = rowk0; c.nt = nt; c.tid = tid; c.r = r; c.h = h; c.sr = swap23(r);
;   c.sK = (u16*)smem; c.sV = c.sK + 2 * C::KBUF;
;   c.init_offs();
;   const int myrow = rowq0 + wave * 32 + r;
;   {
;     const u16* qrow = Qb + (size_t)myrow * qpitch + h * 8;
; #pragma unroll
;     for (int ks = 0; ks < C::NKS; ++ks) c.qf[ks] = __builtin_bit_cast(bf16x8, ldg16(qrow + ks * 16));
;   }
; #pragma unroll
;   for (int a = 0; a < 2; ++a)
; #pragma unroll
;     for (int i = 0; i < 16; ++i) c.o[a][i] = 0.f;
;   c.mref = 0.f; c.l = 0.f;
;   {
;     u32x4 k1 = {h == 0 ? 0x3F80u : 0u, 0u, 0u, 0u}, z4 = {0u, 0u, 0u, 0u};
;     c.kone = __builtin_bit_cast(bf16x8, k1); c.qm = __builtin_bit_cast(bf16x8, z4);
;   }
.LBB0_208:
	s_and_b64 vcc, exec, s[0:1]
	s_cbranch_vccz .LBB0_382
	s_add_u32 s0, s68, 0x2e80800
	s_addc_u32 s1, s69, 0
	s_add_u32 s10, s68, 0x2c20000
	v_writelane_b32 v254, s0, 43
	s_addc_u32 s11, s69, 0
	s_cmp_gt_i32 s18, 1
	v_writelane_b32 v254, s1, 44
	s_mov_b64 s[0:1], -1
	s_cbranch_scc0 .LBB0_333
	s_cmp_gt_i32 s18, 2
	s_cbranch_scc0 .LBB0_296
	v_writelane_b32 v254, s10, 45
	s_add_u32 s55, s68, 0x2f87c00
	s_mov_b32 s0, s53
	v_writelane_b32 v254, s11, 46
	v_writelane_b32 v254, s40, 47
	s_addc_u32 s53, s69, 0
	s_add_u32 s54, s68, 0x101f7c00
	v_writelane_b32 v254, s41, 48
	v_writelane_b32 v254, s18, 49
	v_writelane_b32 v254, s83, 50
	v_writelane_b32 v254, s76, 51
	v_writelane_b32 v254, s64, 52
	v_writelane_b32 v254, s58, 53
	v_writelane_b32 v254, s35, 54
	v_writelane_b32 v254, s88, 55
	s_getreg_b32 s1, hwreg(HW_REG_XCC_ID, 0, 4)
	v_lshlrev_b32_e32 v2, 1, v246
	v_writelane_b32 v254, s89, 56
	v_writelane_b32 v254, s80, 57
	v_lshrrev_b32_e32 v3, 1, v245
	v_add_u32_e32 v5, 0x100, v245
	v_writelane_b32 v254, s81, 58
	v_writelane_b32 v254, s82, 59
	v_writelane_b32 v254, s83, 60
	s_addc_u32 s80, s69, 0
	s_add_u32 s81, s68, 0x142b7c00
	s_addc_u32 s64, s69, 0
	s_add_u32 s58, s68, 0x146c3c00
	s_addc_u32 s52, s69, 0
	s_add_u32 s33, s68, 0x18783c00
	s_addc_u32 s94, s69, 0
	s_add_u32 s95, s68, 0x1c843c00
	s_addc_u32 s93, s69, 0
	s_add_u32 s36, s68, 0x1d873c00
	v_writelane_b32 v254, s1, 61
	s_addc_u32 s37, s69, 0
	v_writelane_b32 v254, s0, 62
	s_lshl_b32 s0, s0, 5
	s_ashr_i32 s1, s0, 31
	s_lshl_b64 s[0:1], s[0:1], 2
	s_add_u32 s2, s68, s0
	v_and_b32_e32 v0, 19, v245
	v_and_b32_e32 v2, 8, v2
	v_and_b32_e32 v3, 4, v3
	v_ashrrev_i32_e32 v6, 31, v5
	s_addc_u32 s3, s69, s1
	v_or3_b32 v2, v3, v0, v2
	v_ashrrev_i32_e32 v0, 31, v245
	v_lshrrev_b32_e32 v6, 29, v6
	s_and_b64 s[0:1], s[30:31], exec
	v_lshrrev_b32_e32 v0, 29, v0
	v_add_u32_e32 v6, v5, v6
	s_cselect_b32 s0, 64, 0
	v_add_u32_e32 v0, v245, v0
	v_ashrrev_i32_e32 v7, 3, v6
	v_lshlrev_b32_e32 v8, 3, v5
	s_movk_i32 s8, 0x90
	s_mov_b32 s6, 0x10300
	s_add_u32 s0, s2, s0
	v_ashrrev_i32_e32 v3, 3, v0
	v_lshlrev_b32_e32 v4, 3, v245
	v_lshl_add_u32 v186, v7, 6, v8
	v_ashrrev_i32_e32 v8, 3, v245
	v_and_b32_e32 v0, 0xffffff8, v0
	s_addc_u32 s1, s3, 0
	v_lshl_add_u32 v184, v3, 6, v4
	v_and_b32_e32 v4, 56, v4
	v_mul_lo_u32 v9, v8, s6
	v_sub_u32_e32 v0, v245, v0
	v_mul_lo_u32 v3, v3, s8
	s_add_u32 s0, s0, 0x2f83820
	v_or_b32_e32 v188, v9, v4
	v_ashrrev_i32_e32 v9, 3, v5
	v_lshl_add_u32 v248, v0, 4, v3
	v_and_b32_e32 v0, 0xffffff8, v6
	v_writelane_b32 v254, s0, 63
	s_addc_u32 s0, s1, 0
	v_mul_lo_u32 v10, v9, s6
	v_sub_u32_e32 v0, v5, v0
	v_mul_lo_u32 v3, v7, s8
	v_writelane_b32 v255, s0, 0
	v_bfe_u32 v1, v245, 5, 1
	v_or_b32_e32 v190, v10, v4
	v_ashrrev_i32_e32 v10, 1, v245
	s_movk_i32 s0, 0xffe0
	v_lshl_add_u32 v249, v0, 4, v3
	v_lshlrev_b32_e32 v0, 1, v4
	v_and_or_b32 v247, v10, s0, v246
	v_mad_u64_u32 v[194:195], s[0:1], v8, s8, v[0:1]
	v_mad_u64_u32 v[196:197], s[0:1], v9, s8, v[0:1]
	v_mul_u32_u24_e32 v0, 0x48, v2
	v_lshlrev_b32_e32 v3, 4, v1
	v_lshl_add_u32 v195, v0, 1, v3
	v_mul_u32_u24_e32 v0, 0x48, v246
	v_lshl_add_u32 v197, v0, 1, v3
	v_mul_hi_i32 v0, v245, s66
	v_lshlrev_b32_e32 v192, 3, v1
	v_cmp_eq_u32_e64 s[6:7], 0, v1
	v_lshlrev_b32_e32 v198, 2, v1
	v_lshrrev_b32_e32 v1, 31, v0
	v_ashrrev_i32_e32 v0, 1, v0
	v_add_u32_e32 v0, v0, v1
	v_mul_lo_u32 v1, v0, 12
	v_sub_u32_e32 v1, v245, v1
	v_lshlrev_b32_e32 v4, 3, v1
	v_lshlrev_b32_e32 v7, 5, v0
	s_movk_i32 s0, 0xffc0
	v_lshl_add_u32 v6, v0, 9, v4
	v_add3_u32 v4, v4, v7, s0
	v_mul_hi_i32 v7, v5, s66
	v_lshrrev_b32_e32 v8, 31, v7
	v_ashrrev_i32_e32 v7, 1, v7
	v_add_u32_e32 v7, v7, v8
	v_mul_lo_u32 v8, v7, 12
	v_mov_b32_e32 v10, 0x3f80
	v_sub_u32_e32 v5, v5, v8
	v_cndmask_b32_e64 v132, 0, v10, s[6:7]
	v_lshlrev_b32_e32 v8, 3, v5
	v_lshlrev_b32_e32 v10, 5, v7
	v_lshl_add_u32 v9, v7, 9, v8
	v_add3_u32 v8, v8, v10, s0
	v_add_u32_e32 v10, 0x200, v245
	v_mul_hi_i32 v11, v10, s66
	v_lshrrev_b32_e32 v12, 31, v11
	v_ashrrev_i32_e32 v11, 1, v11
	v_add_u32_e32 v11, v11, v12
	v_mul_lo_u32 v12, v11, 12
	v_sub_u32_e32 v10, v10, v12
	v_lshlrev_b32_e32 v12, 3, v10
	v_lshlrev_b32_e32 v14, 5, v11
	s_add_u32 s48, s68, 0x2f42c00
	v_lshl_add_u32 v13, v11, 9, v12
	v_add3_u32 v12, v12, v14, s0
	s_movk_i32 s0, 0xd0
	s_addc_u32 s49, s69, 0
	v_mul_lo_u32 v0, v0, s0
	s_add_u32 s50, s68, 0x2f02000
	v_lshl_add_u32 v250, v1, 4, v0
	v_mul_lo_u32 v0, v7, s0
	s_addc_u32 s51, s69, 0
	v_lshl_add_u32 v251, v5, 4, v0
	v_mul_lo_u32 v0, v11, s0
	v_ashrrev_i32_e32 v189, 31, v188
	v_ashrrev_i32_e32 v191, 31, v190
	v_lshl_add_u32 v252, v10, 4, v0
	v_mul_u32_u24_e32 v0, 0x68, v2
	s_add_u32 s0, s68, 0x1d873e80
	v_lshl_add_u32 v236, v0, 1, v3
	v_mov_b32_e32 v231, -1
	v_cmp_lt_i32_e64 s[8:9], 7, v1
	s_addc_u32 s1, s69, 0
	v_lshlrev_b64 v[0:1], 1, v[188:189]
	v_lshlrev_b64 v[2:3], 1, v[190:191]
	v_cmp_lt_i32_e64 s[10:11], 7, v5
	v_cmp_lt_i32_e64 s[12:13], 7, v10
	v_lshl_add_u64 v[206:207], s[0:1], 0, v[0:1]
	v_lshl_add_u64 v[208:209], s[0:1], 0, v[2:3]
	s_add_u32 s0, s68, 0x146c3e80
	v_cndmask_b32_e64 v200, v6, v4, s[8:9]
	v_cndmask_b32_e64 v202, v9, v8, s[10:11]
	v_cndmask_b32_e64 v204, v13, v12, s[12:13]
	s_addc_u32 s1, s69, 0
	s_mov_b32 s88, 0
	v_cmp_eq_u32_e64 s[4:5], 0, v245
	v_mov_b32_e32 v133, v129
	v_mov_b32_e32 v134, v129
	v_mov_b32_e32 v135, v129
	v_ashrrev_i32_e32 v185, 31, v184
	v_ashrrev_i32_e32 v187, 31, v186
	v_ashrrev_i32_e32 v201, 31, v200
	v_ashrrev_i32_e32 v203, 31, v202
	v_ashrrev_i32_e32 v205, 31, v204
	v_lshl_add_u64 v[210:211], s[0:1], 0, v[0:1]
	v_lshl_add_u64 v[212:213], s[0:1], 0, v[2:3]
	s_branch .LBB0_213

; DI void phase_attn(const Params& p, int layer, char* smem, int* s_item, int tid, bool dry) {
;     ...
;         if (tid == 0) *s_item = atomicAdd(cq + L * 8 + x, 1);
;         __syncthreads();
;         const int j = *s_item;
;         __syncthreads();
;         if (j >= 258 + 260) break;
;         int seq, head, qi, nt;
;         if (j < 258) {
;           const int s2 = j / 129; qi = j - s2 * 129; nt = 257;
;           if (L == 0) { const int sg = x + 8 * s2; seq = sg >> 3; head = sg & 7; }
;           else { seq = x >> 2; head = ((x >> 1) & 1) * 4 + (x & 1) * 2 + s2; }
;         } else {
;           const int jj = j - 258, s4 = jj / 65; qi = jj - s4 * 65; nt = 129;
;           if (L == 0) { const int sg = x + 8 * s4; seq = 2 + (sg >> 3); head = sg & 7; }
;           else { seq = 2 + (x >> 1); head = (x & 1) * 4 + s4; }
;         }
.LBB0_218:
	s_and_saveexec_b64 s[0:1], s[4:5]
	s_cbranch_execz .LBB0_220
	s_waitcnt vmcnt(0)
	v_cmp_gt_i32_e32 vcc, 0, v231
	s_cbranch_vccz .Lq_have
	v_mov_b64_e32 v[0:1], s[42:43]
	flat_atomic_add v231, v[0:1], v222 sc0
	s_waitcnt vmcnt(0) lgkmcnt(0)
.Lq_have:
	ds_write_b32 v225, v231
.LBB0_220:
	s_or_b64 exec, exec, s[0:1]
	s_waitcnt lgkmcnt(0)
	v_mov_b32_e32 v231, -1
	s_barrier
	ds_read_b32 v0, v225
	s_movk_i32 s0, 0x205
	s_waitcnt lgkmcnt(0)
	s_barrier
	v_cmp_lt_i32_e32 vcc, s0, v0
	v_readfirstlane_b32 s15, v0
	s_mov_b64 s[0:1], -1
	s_cbranch_vccnz .LBB0_217
	s_cmpk_gt_i32 s15, 0x101
	s_cbranch_scc0 .LBB0_228
	s_add_i32 s0, s15, 0xfffffefe
	s_mul_i32 s1, s0, 0xfc1
	s_lshr_b32 s14, s1, 18
	s_mul_i32 s1, s14, 0xffffffbf
	s_add_i32 s34, s1, s0
	s_add_i32 s19, s22, s14
	s_and_b64 s[0:1], s[40:41], exec
	s_cselect_b32 s0, s14, s83
	s_cselect_b32 s35, s89, s19
	s_add_i32 s14, s0, 2
	s_movk_i32 s19, 0x81
	s_cbranch_execz .LBB0_229

;   template <int PAR>
;   DI void step(int t, f32x16 (&cur)[2], f32x16 (&nxt)[2]) {
;     ...
;     float psum = 0.f;
; #pragma unroll
;     for (int kb2 = 0; kb2 < 2; ++kb2)
; #pragma unroll
;       for (int i = 0; i < 16; ++i) { const float pv = __builtin_amdgcn_exp2f(cur[kb2][i]); cur[kb2][i] = pv; psum += pv; }
;     l += psum;
; DI void phase_attn(const Params& p, int layer, char* smem, int* s_item, int tid, bool dry) {
;     ...
;         if (tid == 0) *s_item = atomicAdd(cq + L * 8 + x, 1);
.Lg_fold:
	s_mov_b64 exec, s[4:5]
	s_cbranch_execz .Lq_nopfg
	v_mov_b64_e32 v[232:233], s[42:43]
	global_atomic_add v231, v[232:233], v222, off sc0
.Lq_nopfg:
	s_mov_b64 exec, -1
	s_waitcnt lgkmcnt(0)
	v_add_f32_e32 v173, v173, v182
	v_add_f32_e32 v173, v173, v183
	s_branch .LBB0_253

;   template <int PAR>
;   DI void step(int t, f32x16 (&cur)[2], f32x16 (&nxt)[2]) {
;     ...
;     float psum = 0.f;
; #pragma unroll
;     for (int kb2 = 0; kb2 < 2; ++kb2)
; #pragma unroll
;       for (int i = 0; i < 16; ++i) { const float pv = __builtin_amdgcn_exp2f(cur[kb2][i]); cur[kb2][i] = pv; psum += pv; }
;     l += psum;
.Lq_nopfm:
	s_mov_b64 exec, -1
	s_waitcnt lgkmcnt(0)
	v_add_f32_e32 v237, v237, v238
	v_add_f32_e32 v237, v237, v239
	s_branch .LBB0_283
